# adds batched loads in the select-phase K staging, the compression-MLP k-loop and the V-image items (one wait per batch instead of one per load)
# speedup vs baseline: 1.0125x; 1.0077x over previous
; #define LAS __attribute__((address_space(3)))
; #define LDS_WAIT() asm volatile("s_waitcnt lgkmcnt(0)" ::: "memory")
; __device__ __forceinline__ int hs_dil(int hs) { return (hs >= 14 && hs < 17) ? 4 : ((hs >= 17 && hs < 20) ? 16 : 1); }
; __device__ __forceinline__ size_t vtb_off(int b, int hs, int kb) { return ((size_t)(b * NHS + hs) * VTB_KB + kb) * 4096; }
; __device__ __forceinline__ void vprep_item(const bf16* PROJ, unsigned char* VTB, int item, LAS unsigned* s32, int lane) {
;     const int kb = item % VTB_KB, hs = (item / VTB_KB) % NHS, b = item / (VTB_KB * NHS);
;     const int dil = hs_dil(hs), col = hs_col(hs), tk = lane & 31, half = lane >> 5;
;     const int pos = kb * 32 + tk, seg = SEQ / dil, token = pos / seg + dil * (pos % seg);
;     const v4u* src = (const v4u*)(PROJ + ((size_t)b * SEQ + token) * NINP + col + 32 * half);
; #pragma unroll
;     for (int i = 0; i < 4; ++i) { const v4u w = src[i]; LAS unsigned* d = s32 + tk * 33 + 16 * half + 4 * i; d[0] = w.x; d[1] = w.y; d[2] = w.z; d[3] = w.w; }
;     LDS_WAIT(); asm volatile("" ::: "memory");
;     const LAS unsigned short* s16 = (const LAS unsigned short*)s32;
;     unsigned out[16];
; #pragma unroll
;     for (int p = 0; p < 32; p += 2) { const unsigned lo = s16[vtb_key_of_pos(p) * 66 + 32 * half + tk], hi = s16[vtb_key_of_pos(p + 1) * 66 + 32 * half + tk]; out[p >> 1] = lo | (hi << 16); }
;     v4u* dst = (v4u*)(VTB + vtb_off(b, hs, kb) + half * 2048 + tk * 64);
; #pragma unroll
;     for (int i = 0; i < 4; ++i) { v4u w; w.x = out[4 * i]; w.y = out[4 * i + 1]; w.z = out[4 * i + 2]; w.w = out[4 * i + 3]; dst[i] = w; }
;     LDS_WAIT(); asm volatile("" ::: "memory");
.LBB0_373:
	s_mul_hi_i32 s2, s4, 0x92492493
	s_add_i32 s2, s2, s4
	s_lshr_b32 s13, s2, 31
	s_ashr_i32 s2, s2, 11
	s_add_i32 s14, s2, s13
	s_lshl_b32 s2, s11, 7
	s_sub_i32 s3, s10, 17
	s_add_i32 s12, s10, -14
	s_sub_i32 s2, s4, s2
	s_lshl_b32 s11, s11, 12
	s_cmp_lt_u32 s3, 3
	s_movk_i32 s3, 0x100
	s_cselect_b32 s3, s3, 0x1000
	s_cselect_b32 s13, 4, 0
	s_cmp_lt_u32 s12, 3
	s_cselect_b32 s3, 0x400, s3
	s_cselect_b32 s12, 2, s13
	s_abs_i32 s13, s3
	v_cvt_f32_u32_e32 v11, s13
	v_subrev_u32_e32 v12, s11, v9
	s_sub_i32 s11, 0, s13
	v_sub_u32_e32 v14, 0, v12
	v_rcp_iflag_f32_e32 v11, v11
	v_max_i32_e32 v14, v12, v14
	v_xor_b32_e32 v13, s3, v12
	v_ashrrev_i32_e32 v13, 31, v13
	v_mul_f32_e32 v11, 0x4f7ffffe, v11
	v_cvt_u32_f32_e32 v11, v11
	s_ashr_i32 s15, s14, 31
	s_ashr_i32 s17, s16, 31
	v_add_u32_e32 v9, s9, v9
	v_mul_lo_u32 v15, s11, v11
	v_mul_hi_u32 v15, v11, v15
	v_add_u32_e32 v11, v11, v15
	v_mul_hi_u32 v11, v14, v11
	v_mul_lo_u32 v15, v11, s13
	v_sub_u32_e32 v14, v14, v15
	v_add_u32_e32 v15, 1, v11
	v_cmp_le_u32_e32 vcc, s13, v14
	s_nop 1
	v_cndmask_b32_e32 v11, v11, v15, vcc
	v_subrev_u32_e32 v15, s13, v14
	v_cndmask_b32_e32 v14, v14, v15, vcc
	v_add_u32_e32 v15, 1, v11
	v_cmp_le_u32_e32 vcc, s13, v14
	s_nop 1
	v_cndmask_b32_e32 v11, v11, v15, vcc
	v_xor_b32_e32 v11, v11, v13
	v_sub_u32_e32 v11, v11, v13
	v_mul_lo_u32 v13, v11, s3
	v_sub_u32_e32 v12, v12, v13
	v_lshl_add_u32 v12, v12, s12, v11
	s_lshl_b64 s[12:13], s[14:15], 12
	v_ashrrev_i32_e32 v13, 31, v12
	v_lshl_add_u64 v[12:13], s[12:13], 0, v[12:13]
	v_mov_b64_e32 v[14:15], s[52:53]
	v_mad_u64_u32 v[14:15], s[12:13], v12, s83, v[14:15]
	v_mad_i32_i24 v15, v13, s83, v15
	v_lshl_add_u64 v[12:13], s[16:17], 1, v[14:15]
	v_lshl_add_u64 v[16:17], v[12:13], 0, v[2:3]
	flat_load_dwordx4 v[12:15], v[16:17]
	flat_load_dwordx4 v[146:149], v[16:17] offset:16
	flat_load_dwordx4 v[150:153], v[16:17] offset:32
	flat_load_dwordx4 v[154:157], v[16:17] offset:48
	s_mul_i32 s3, s14, 28
	s_add_i32 s10, s3, s10
	s_ashr_i32 s3, s2, 31
	s_ashr_i32 s11, s10, 31
	s_lshl_b64 s[2:3], s[2:3], 12
	s_lshl_b64 s[10:11], s[10:11], 19
	s_add_u32 s10, s7, s10
	s_addc_u32 s11, s8, s11
	s_add_u32 s2, s10, s2
	s_addc_u32 s3, s11, s3
	s_add_i32 s4, s4, s6
	s_cmpk_lt_i32 s4, 0x1c00
	s_waitcnt vmcnt(0) lgkmcnt(0)
	ds_write2_b32 v10, v12, v13 offset1:1
	ds_write2_b32 v10, v14, v15 offset0:2 offset1:3
	ds_write2_b32 v10, v146, v147 offset0:4 offset1:5
	ds_write2_b32 v10, v148, v149 offset0:6 offset1:7
	ds_write2_b32 v10, v150, v151 offset0:8 offset1:9
	ds_write2_b32 v10, v152, v153 offset0:10 offset1:11
	v_lshl_add_u64 v[16:17], s[2:3], 0, v[4:5]
	v_lshl_add_u64 v[28:29], v[16:17], 0, v[6:7]
	ds_write2_b32 v10, v154, v155 offset0:12 offset1:13
	ds_write2_b32 v10, v156, v157 offset0:14 offset1:15
	s_waitcnt lgkmcnt(0)
	ds_read_u16 v11, v8
	ds_read_u16 v12, v8 offset:132
	ds_read_u16 v13, v8 offset:264
	ds_read_u16 v14, v8 offset:396
	ds_read_u16 v16, v8 offset:528
	ds_read_u16 v17, v8 offset:660
	ds_read_u16 v18, v8 offset:792
	ds_read_u16 v19, v8 offset:924
	ds_read_u16 v15, v8 offset:1056
	ds_read_u16 v20, v8 offset:1188
	ds_read_u16 v21, v8 offset:1320
	ds_read_u16 v22, v8 offset:1452
	ds_read_u16 v23, v8 offset:1584
	ds_read_u16 v24, v8 offset:1716
	ds_read_u16 v25, v8 offset:1848
	ds_read_u16 v26, v8 offset:1980
	ds_read_u16 v27, v8 offset:2112
	ds_read_u16 v30, v8 offset:2244
	ds_read_u16 v31, v8 offset:2376
	ds_read_u16 v32, v8 offset:2508
	ds_read_u16 v33, v8 offset:2640
	ds_read_u16 v34, v8 offset:2772
	ds_read_u16 v35, v8 offset:2904
	ds_read_u16 v36, v8 offset:3036
	ds_read_u16 v37, v8 offset:3168
	ds_read_u16 v38, v8 offset:3300
	ds_read_u16 v39, v8 offset:3432
	ds_read_u16 v40, v8 offset:3564
	ds_read_u16 v41, v8 offset:3696
	ds_read_u16 v42, v8 offset:3828
	ds_read_u16 v43, v8 offset:3960
	ds_read_u16 v44, v8 offset:4092
	s_waitcnt lgkmcnt(14)
	v_lshl_or_b32 v12, v12, 16, v11
	v_lshl_or_b32 v13, v14, 16, v13
	v_lshl_or_b32 v14, v20, 16, v15
	v_lshl_or_b32 v15, v22, 16, v21
	v_lshl_or_b32 v16, v17, 16, v16
	v_lshl_or_b32 v17, v19, 16, v18
	v_lshl_or_b32 v18, v24, 16, v23
	v_lshl_or_b32 v19, v26, 16, v25
	v_lshl_or_b32 v20, v30, 16, v27
	s_waitcnt lgkmcnt(12)
	v_lshl_or_b32 v21, v32, 16, v31
	s_waitcnt lgkmcnt(6)
	v_lshl_or_b32 v22, v38, 16, v37
	s_waitcnt lgkmcnt(4)
	v_lshl_or_b32 v23, v40, 16, v39
	v_lshl_or_b32 v24, v34, 16, v33
	v_lshl_or_b32 v25, v36, 16, v35
	s_waitcnt lgkmcnt(2)
	v_lshl_or_b32 v26, v42, 16, v41
	s_waitcnt lgkmcnt(0)
	v_lshl_or_b32 v27, v44, 16, v43
	flat_store_dwordx4 v[28:29], v[12:15]
	flat_store_dwordx4 v[28:29], v[16:19] offset:16
	flat_store_dwordx4 v[28:29], v[20:23] offset:32
	flat_store_dwordx4 v[28:29], v[24:27] offset:48
	s_waitcnt lgkmcnt(0)
	s_cbranch_scc0 .LBB0_390

; #define LAS __attribute__((address_space(3)))
; #define LDS_WAIT() asm volatile("s_waitcnt lgkmcnt(0)" ::: "memory")
; __device__ __forceinline__ int hs_dil(int hs) { return (hs >= 14 && hs < 17) ? 4 : ((hs >= 17 && hs < 20) ? 16 : 1); }
; __device__ __forceinline__ size_t vtb_off(int b, int hs, int kb) { return ((size_t)(b * NHS + hs) * VTB_KB + kb) * 4096; }
; __device__ __forceinline__ void vprep_item(const bf16* PROJ, unsigned char* VTB, int item, LAS unsigned* s32, int lane) {
;     const int kb = item % VTB_KB, hs = (item / VTB_KB) % NHS, b = item / (VTB_KB * NHS);
;     const int dil = hs_dil(hs), col = hs_col(hs), tk = lane & 31, half = lane >> 5;
;     const int pos = kb * 32 + tk, seg = SEQ / dil, token = pos / seg + dil * (pos % seg);
;     const v4u* src = (const v4u*)(PROJ + ((size_t)b * SEQ + token) * NINP + col + 32 * half);
; #pragma unroll
;     for (int i = 0; i < 4; ++i) { const v4u w = src[i]; LAS unsigned* d = s32 + tk * 33 + 16 * half + 4 * i; d[0] = w.x; d[1] = w.y; d[2] = w.z; d[3] = w.w; }
;     LDS_WAIT(); asm volatile("" ::: "memory");
;     const LAS unsigned short* s16 = (const LAS unsigned short*)s32;
;     unsigned out[16];
; #pragma unroll
;     for (int p = 0; p < 32; p += 2) { const unsigned lo = s16[vtb_key_of_pos(p) * 66 + 32 * half + tk], hi = s16[vtb_key_of_pos(p + 1) * 66 + 32 * half + tk]; out[p >> 1] = lo | (hi << 16); }
;     v4u* dst = (v4u*)(VTB + vtb_off(b, hs, kb) + half * 2048 + tk * 64);
; #pragma unroll
;     for (int i = 0; i < 4; ++i) { v4u w; w.x = out[4 * i]; w.y = out[4 * i + 1]; w.z = out[4 * i + 2]; w.w = out[4 * i + 3]; dst[i] = w; }
;     LDS_WAIT(); asm volatile("" ::: "memory");
.LBB0_395:
	s_mul_hi_i32 s12, s4, 0x92492493
	s_add_i32 s12, s12, s4
	s_lshr_b32 s13, s12, 31
	s_ashr_i32 s12, s12, 11
	s_add_i32 s16, s12, s13
	s_lshl_b32 s12, s3, 7
	s_sub_i32 s10, s9, 17
	s_add_i32 s11, s9, -14
	s_sub_i32 s14, s4, s12
	s_lshl_b32 s3, s3, 12
	s_cmp_lt_u32 s10, 3
	s_movk_i32 s10, 0x100
	s_cselect_b32 s10, s10, 0x1000
	s_cselect_b32 s12, 4, 0
	s_cmp_lt_u32 s11, 3
	s_cselect_b32 s10, 0x400, s10
	s_cselect_b32 s11, 2, s12
	s_abs_i32 s12, s10
	v_cvt_f32_u32_e32 v10, s12
	v_subrev_u32_e32 v11, s3, v8
	s_sub_i32 s3, 0, s12
	v_sub_u32_e32 v13, 0, v11
	v_rcp_iflag_f32_e32 v10, v10
	v_max_i32_e32 v13, v11, v13
	v_xor_b32_e32 v12, s10, v11
	v_ashrrev_i32_e32 v12, 31, v12
	v_mul_f32_e32 v10, 0x4f7ffffe, v10
	v_cvt_u32_f32_e32 v10, v10
	s_ashr_i32 s17, s16, 31
	s_ashr_i32 s15, s14, 31
	v_add_u32_e32 v8, s8, v8
	v_mul_lo_u32 v14, s3, v10
	v_mul_hi_u32 v14, v10, v14
	v_add_u32_e32 v10, v10, v14
	v_mul_hi_u32 v10, v13, v10
	v_mul_lo_u32 v14, v10, s12
	v_sub_u32_e32 v13, v13, v14
	v_add_u32_e32 v14, 1, v10
	v_cmp_le_u32_e32 vcc, s12, v13
	s_ashr_i32 s3, s2, 31
	s_nop 0
	v_cndmask_b32_e32 v10, v10, v14, vcc
	v_subrev_u32_e32 v14, s12, v13
	v_cndmask_b32_e32 v13, v13, v14, vcc
	v_add_u32_e32 v14, 1, v10
	v_cmp_le_u32_e32 vcc, s12, v13
	s_nop 1
	v_cndmask_b32_e32 v10, v10, v14, vcc
	v_xor_b32_e32 v10, v10, v12
	v_sub_u32_e32 v10, v10, v12
	v_mul_lo_u32 v12, v10, s10
	v_sub_u32_e32 v11, v11, v12
	v_lshl_add_u32 v10, v11, s11, v10
	s_lshl_b64 s[10:11], s[16:17], 12
	v_ashrrev_i32_e32 v11, 31, v10
	v_lshl_add_u64 v[10:11], s[10:11], 0, v[10:11]
	v_mov_b64_e32 v[12:13], s[52:53]
	v_mad_u64_u32 v[12:13], s[10:11], v10, s83, v[12:13]
	v_mad_i32_i24 v13, v11, s83, v13
	v_lshl_add_u64 v[10:11], s[2:3], 1, v[12:13]
	v_lshl_add_u64 v[14:15], v[10:11], 0, v[2:3]
	flat_load_dwordx4 v[10:13], v[14:15]
	flat_load_dwordx4 v[146:149], v[14:15] offset:16
	flat_load_dwordx4 v[150:153], v[14:15] offset:32
	flat_load_dwordx4 v[154:157], v[14:15] offset:48
	s_mul_i32 s2, s16, 28
	s_add_i32 s2, s2, s9
	s_ashr_i32 s3, s2, 31
	s_lshl_b64 s[10:11], s[14:15], 12
	s_lshl_b64 s[2:3], s[2:3], 19
	s_add_u32 s2, s6, s2
	s_addc_u32 s3, s7, s3
	s_add_u32 s2, s2, s10
	s_addc_u32 s3, s3, s11
	s_add_i32 s4, s4, s5
	s_cmpk_gt_i32 s4, 0x1bff
	s_waitcnt vmcnt(0) lgkmcnt(0)
	ds_write2_b32 v9, v10, v11 offset1:1
	ds_write2_b32 v9, v12, v13 offset0:2 offset1:3
	ds_write2_b32 v9, v146, v147 offset0:4 offset1:5
	ds_write2_b32 v9, v148, v149 offset0:6 offset1:7
	ds_write2_b32 v9, v150, v151 offset0:8 offset1:9
	ds_write2_b32 v9, v152, v153 offset0:10 offset1:11
	v_lshl_add_u64 v[14:15], s[2:3], 0, v[4:5]
	v_lshl_add_u64 v[26:27], v[14:15], 0, v[6:7]
	ds_write2_b32 v9, v154, v155 offset0:12 offset1:13
	ds_write2_b32 v9, v156, v157 offset0:14 offset1:15
	s_waitcnt lgkmcnt(0)
	ds_read_u16 v10, v1
	ds_read_u16 v11, v1 offset:132
	ds_read_u16 v12, v1 offset:264
	ds_read_u16 v13, v1 offset:396
	ds_read_u16 v14, v1 offset:528
	ds_read_u16 v15, v1 offset:660
	ds_read_u16 v16, v1 offset:792
	ds_read_u16 v17, v1 offset:924
	ds_read_u16 v18, v1 offset:1056
	ds_read_u16 v19, v1 offset:1188
	ds_read_u16 v20, v1 offset:1320
	ds_read_u16 v21, v1 offset:1452
	ds_read_u16 v22, v1 offset:1584
	ds_read_u16 v23, v1 offset:1716
	ds_read_u16 v24, v1 offset:1848
	ds_read_u16 v25, v1 offset:1980
	ds_read_u16 v28, v1 offset:2112
	ds_read_u16 v29, v1 offset:2244
	ds_read_u16 v30, v1 offset:2376
	ds_read_u16 v31, v1 offset:2508
	ds_read_u16 v32, v1 offset:2640
	ds_read_u16 v33, v1 offset:2772
	ds_read_u16 v34, v1 offset:2904
	ds_read_u16 v35, v1 offset:3036
	ds_read_u16 v36, v1 offset:3168
	ds_read_u16 v37, v1 offset:3300
	ds_read_u16 v38, v1 offset:3432
	ds_read_u16 v39, v1 offset:3564
	ds_read_u16 v40, v1 offset:3696
	ds_read_u16 v41, v1 offset:3828
	ds_read_u16 v42, v1 offset:3960
	ds_read_u16 v43, v1 offset:4092
	s_waitcnt lgkmcnt(14)
	v_lshl_or_b32 v10, v11, 16, v10
	v_lshl_or_b32 v11, v13, 16, v12
	v_lshl_or_b32 v12, v19, 16, v18
	v_lshl_or_b32 v13, v21, 16, v20
	v_lshl_or_b32 v14, v15, 16, v14
	v_lshl_or_b32 v15, v17, 16, v16
	v_lshl_or_b32 v16, v23, 16, v22
	v_lshl_or_b32 v17, v25, 16, v24
	v_lshl_or_b32 v18, v29, 16, v28
	s_waitcnt lgkmcnt(12)
	v_lshl_or_b32 v19, v31, 16, v30
	s_waitcnt lgkmcnt(6)
	v_lshl_or_b32 v20, v37, 16, v36
	s_waitcnt lgkmcnt(4)
	v_lshl_or_b32 v21, v39, 16, v38
	v_lshl_or_b32 v22, v33, 16, v32
	v_lshl_or_b32 v23, v35, 16, v34
	s_waitcnt lgkmcnt(2)
	v_lshl_or_b32 v24, v41, 16, v40
	s_waitcnt lgkmcnt(0)
	v_lshl_or_b32 v25, v43, 16, v42
	flat_store_dwordx4 v[26:27], v[10:13]
	flat_store_dwordx4 v[26:27], v[14:17] offset:16
	flat_store_dwordx4 v[26:27], v[18:21] offset:32
	flat_store_dwordx4 v[26:27], v[22:25] offset:48
	s_waitcnt lgkmcnt(0)
	s_cbranch_scc1 .LBB0_412

; #define GAS __attribute__((address_space(1)))
; #define LAS __attribute__((address_space(3)))
; #define MFMA32(a, b, c) __builtin_amdgcn_mfma_f32_32x32x16_bf16((a), (b), (c), 0, 0, 0)
; __device__ __forceinline__ void compress_item_mfma(const bf16* PROJ, const bf16* W1T, const bf16* W2T, const float* PW1, bf16* KC, unsigned char* VCB, int it, LAS unsigned char* lds, int wave, int lane) {
;     ...
; #pragma unroll 4
;     for (int s = 16 * wave; s < 16 * wave + 16; ++s) { int tok = tokbase + (s >> 2); tok = tok < SEQ ? tok : SEQ - 1;
;         const bf16x8 bfr = *(const GAS bf16x8*)(PROJ + ((size_t)b * SEQ + tok) * NINP + colbase + 16 * (s & 3) + 8 * hh);
;         const bf16x8 a0 = *(const GAS bf16x8*)(w1t + 16 * s), a1 = *(const GAS bf16x8*)(w1t + (size_t)32 * 2048 + 16 * s);
;         hT[0] = MFMA32(a0, bfr, hT[0]); hT[1] = MFMA32(a1, bfr, hT[1]); }
;     LAS float* part = (LAS float*)lds;
; #pragma unroll
;     for (int nt = 0; nt < 2; ++nt)
; #pragma unroll
;         for (int r = 0; r < 16; ++r) part[(wave * 32 + nt * 16 + r) * 64 + lane] = hT[nt][r];
.LBB0_428:
	s_ashr_i32 s13, s12, 2
	v_add_u32_e32 v41, s13, v40
	v_lshl_add_u64 v[66:67], v[38:39], 0, s[20:21]
	s_mov_b32 s13, 0x500000
	v_add_co_u32_e32 v70, vcc, s13, v66
	s_mov_b32 s13, 0x520000
	s_nop 0
	v_addc_co_u32_e32 v71, vcc, 0, v67, vcc
	v_add_co_u32_e32 v72, vcc, s13, v66
	s_nop 1
	v_addc_co_u32_e32 v73, vcc, 0, v67, vcc
	v_min_i32_e32 v41, 0xfff, v41
	v_add_u32_e32 v41, s4, v41
	v_mad_i64_i32 v[46:47], s[30:31], v41, s83, v[36:37]
	global_load_dwordx4 v[146:149], v[70:71], off
	global_load_dwordx4 v[150:153], v[72:73], off
	global_load_dwordx4 v[154:157], v[46:47], off
	global_load_dwordx4 v[158:161], v[70:71], off offset:32
	global_load_dwordx4 v[162:165], v[72:73], off offset:32
	global_load_dwordx4 v[166:169], v[46:47], off offset:32
	global_load_dwordx4 v[170:173], v[70:71], off offset:64
	global_load_dwordx4 v[174:177], v[72:73], off offset:64
	global_load_dwordx4 v[178:181], v[46:47], off offset:64
	global_load_dwordx4 v[182:185], v[70:71], off offset:96
	global_load_dwordx4 v[214:217], v[72:73], off offset:96
	global_load_dwordx4 v[218:221], v[46:47], off offset:96
	s_add_i32 s12, s12, 4
	s_add_u32 s20, s20, 0x80
	s_addc_u32 s21, s21, 0
	s_cmpk_eq_i32 s20, 0x200
	s_waitcnt vmcnt(9)
	v_mfma_f32_32x32x16_bf16 v[20:35], v[146:149], v[154:157], v[20:35]
	v_mfma_f32_32x32x16_bf16 v[4:19], v[150:153], v[154:157], v[4:19]
	s_waitcnt vmcnt(6)
	v_mfma_f32_32x32x16_bf16 v[20:35], v[158:161], v[166:169], v[20:35]
	v_mfma_f32_32x32x16_bf16 v[4:19], v[162:165], v[166:169], v[4:19]
	s_waitcnt vmcnt(3)
	v_mfma_f32_32x32x16_bf16 v[20:35], v[170:173], v[178:181], v[20:35]
	v_mfma_f32_32x32x16_bf16 v[4:19], v[174:177], v[178:181], v[4:19]
	s_waitcnt vmcnt(0)
	v_mfma_f32_32x32x16_bf16 v[20:35], v[182:185], v[218:221], v[20:35]
	v_mfma_f32_32x32x16_bf16 v[4:19], v[214:217], v[218:221], v[4:19]
	s_cbranch_scc0 .LBB0_428
	v_add_u32_e32 v36, s10, v60
	s_andn2_b64 vcc, exec, s[14:15]
	s_nop 6
	ds_write2st64_b32 v36, v20, v21 offset1:1
	ds_write2st64_b32 v36, v22, v23 offset0:2 offset1:3
	ds_write2st64_b32 v36, v24, v25 offset0:4 offset1:5
	ds_write2st64_b32 v36, v26, v27 offset0:6 offset1:7
	ds_write2st64_b32 v36, v28, v29 offset0:8 offset1:9
	ds_write2st64_b32 v36, v30, v31 offset0:10 offset1:11
	ds_write2st64_b32 v36, v32, v33 offset0:12 offset1:13
	ds_write2st64_b32 v36, v34, v35 offset0:14 offset1:15
	ds_write2st64_b32 v36, v4, v5 offset0:16 offset1:17
	ds_write2st64_b32 v36, v6, v7 offset0:18 offset1:19
	ds_write2st64_b32 v36, v8, v9 offset0:20 offset1:21
	ds_write2st64_b32 v36, v10, v11 offset0:22 offset1:23
	ds_write2st64_b32 v36, v12, v13 offset0:24 offset1:25
	ds_write2st64_b32 v36, v14, v15 offset0:26 offset1:27
	ds_write2st64_b32 v36, v16, v17 offset0:28 offset1:29
	ds_write2st64_b32 v36, v18, v19 offset0:30 offset1:31
	s_waitcnt lgkmcnt(0)
	s_barrier
	s_cbranch_vccnz .LBB0_426
	s_movk_i32 s4, 0x2000

; #define GAS __attribute__((address_space(1)))
; #define LAS __attribute__((address_space(3)))
; __device__ __forceinline__ void nsa_select_coop(const bf16* PROJ, const bf16* KC, unsigned long long* SEL, LAS unsigned char* lds, int pair, int tid) {
;     ...
;     {   const int tmx = 32 * ((2 * pair + 1) & 127) + 31; int nc = tmx >= 31 ? ((tmx - 31) >> 4) + 1 : 0; nc = nc > 255 ? 255 : nc; const int nrow = 32 * ((nc + 31) >> 5);
;         const GAS v4u* src = (const GAS v4u*)(KC + (size_t)((0 * BATCH + b) * 2 + g) * 256 * 64);
;         for (int i = tid; i < nrow * 8; i += NWAVES * 64) { const int rw = i >> 3, c = i & 7; *(LAS v4u*)(kl + rw * 128 + ((c ^ ((rw >> 1) & 7)) << 4)) = src[i]; } }
.LBB0_483:
	s_mov_b64 s[10:11], 0x2000
	global_load_dwordx4 v[10:13], v[6:7], off
	v_bitop3_b32 v14, v5, s85, v8 bitop3:0x48
	v_and_b32_e32 v9, 0xffffff80, v5
	v_add3_u32 v9, s8, v9, v14
	v_add_u32_e32 v8, 0x200, v8
	v_add_u32_e32 v5, 0x2000, v5
	v_lshl_add_u64 v[6:7], v[6:7], 0, s[10:11]
	v_cmp_gt_i32_e32 vcc, s4, v8
	s_and_saveexec_b64 s[30:31], vcc
	global_load_dwordx4 v[146:149], v[6:7], off
	v_bitop3_b32 v14, v5, s85, v8 bitop3:0x48
	v_and_b32_e32 v150, 0xffffff80, v5
	v_add3_u32 v150, s8, v150, v14
	v_add_u32_e32 v8, 0x200, v8
	v_add_u32_e32 v5, 0x2000, v5
	v_lshl_add_u64 v[6:7], v[6:7], 0, s[10:11]
	v_cmp_gt_i32_e32 vcc, s4, v8
	s_and_saveexec_b64 s[32:33], vcc
	global_load_dwordx4 v[152:155], v[6:7], off
	v_bitop3_b32 v14, v5, s85, v8 bitop3:0x48
	v_and_b32_e32 v151, 0xffffff80, v5
	v_add3_u32 v151, s8, v151, v14
	v_add_u32_e32 v8, 0x200, v8
	v_add_u32_e32 v5, 0x2000, v5
	v_lshl_add_u64 v[6:7], v[6:7], 0, s[10:11]
	v_cmp_gt_i32_e32 vcc, s4, v8
	s_and_saveexec_b64 s[62:63], vcc
	global_load_dwordx4 v[156:159], v[6:7], off
	v_bitop3_b32 v14, v5, s85, v8 bitop3:0x48
	v_and_b32_e32 v160, 0xffffff80, v5
	v_add3_u32 v160, s8, v160, v14
	s_waitcnt vmcnt(0)
	ds_write_b128 v160, v[156:159]
	s_mov_b64 exec, s[62:63]
	ds_write_b128 v151, v[152:155]
	s_mov_b64 exec, s[32:33]
	ds_write_b128 v150, v[146:149]
	s_mov_b64 exec, s[30:31]
	ds_write_b128 v9, v[10:13]
